# hgrn_u publishes U/d with agent-scope write-through stores instead of a per-workgroup L2 writeback (buffer_wbl2)
# speedup vs baseline: 1.0244x; 1.0244x over previous
.LBB0_534:
	s_add_i32 s2, s60, s14
	s_cmpk_lt_i32 s2, 0x200
	s_cselect_b32 s2, s2, -1
	s_cmp_gt_i32 s2, -1
	s_cselect_b64 s[36:37], -1, 0
	s_and_b64 s[18:19], s[36:37], exec
	v_mov_b32_e32 v190, v184
	s_cselect_b32 s68, s2, s14
	s_ashr_i32 s18, s14, 7
	s_ashr_i32 s19, s18, 31
	v_ashrrev_i32_e32 v9, 6, v190
	v_lshlrev_b32_e32 v6, 4, v9
	s_lshl_b64 s[44:45], s[18:19], 12
	s_and_b32 s2, s13, 0xf80
	v_ashrrev_i32_e32 v7, 31, v6
	s_or_b32 s44, s44, s2
	v_lshl_add_u64 v[4:5], s[44:45], 0, v[6:7]
	v_lshlrev_b64 v[0:1], 10, v[4:5]
	s_and_b32 s2, s12, 0xc0
	v_and_b32_e32 v8, 63, v190
	v_lshl_add_u64 v[0:1], s[26:27], 0, v[0:1]
	s_lshl_b32 s80, s2, 2
	v_lshl_add_u64 v[2:3], v[0:1], 0, s[80:81]
	v_lshlrev_b32_e32 v0, 2, v8
	v_mov_b32_e32 v1, v191
	v_lshl_add_u64 v[10:11], v[2:3], 0, v[0:1]
	v_mov_b64_e32 v[2:3], s[22:23]
	v_mad_u64_u32 v[12:13], s[18:19], v4, s70, v[2:3]
	v_add_co_u32_e32 v14, vcc, s76, v10
	s_ashr_i32 s18, s68, 7
	s_nop 0
	v_addc_co_u32_e32 v15, vcc, 0, v11, vcc
	s_lshl_b32 s80, s2, 1
	v_add_co_u32_e32 v16, vcc, s65, v10
	s_ashr_i32 s19, s18, 31
	s_lshl_b32 s2, s68, 7
	v_addc_co_u32_e32 v17, vcc, 0, v11, vcc
	s_lshl_b64 s[40:41], s[18:19], 12
	s_and_b32 s2, s2, 0xf80
	global_load_dword v24, v[10:11], off
	global_load_dword v25, v[10:11], off offset:1024
	global_load_dword v26, v[10:11], off offset:2048
	global_load_dword v27, v[10:11], off offset:3072
	v_add_co_u32_e32 v10, vcc, s73, v10
	s_or_b32 s40, s40, s2
	s_nop 0
	v_addc_co_u32_e32 v11, vcc, 0, v11, vcc
	v_lshl_add_u64 v[6:7], s[40:41], 0, v[6:7]
	s_lshl_b32 s2, s68, 1
	global_load_dword v28, v[16:17], off offset:-4096
	global_load_dword v29, v[14:15], off offset:1024
	global_load_dword v30, v[14:15], off offset:2048
	global_load_dword v31, v[14:15], off offset:3072
	global_load_dword v32, v[16:17], off
	global_load_dword v33, v[16:17], off offset:1024
	global_load_dword v34, v[16:17], off offset:2048
	global_load_dword v35, v[16:17], off offset:3072
	global_load_dword v36, v[10:11], off
	global_load_dword v37, v[10:11], off offset:1024
	global_load_dword v38, v[10:11], off offset:2048
	global_load_dword v39, v[10:11], off offset:3072
	v_lshlrev_b64 v[10:11], 10, v[6:7]
	s_and_b32 s2, s2, 0xc0
	v_lshl_add_u64 v[10:11], s[26:27], 0, v[10:11]
	s_lshl_b32 s18, s2, 2
	s_mov_b32 s19, s81
	v_lshl_add_u64 v[10:11], v[10:11], 0, s[18:19]
	v_lshl_add_u64 v[22:23], v[10:11], 0, v[0:1]
	v_mad_u64_u32 v[10:11], s[18:19], v6, s70, v[2:3]
	v_mad_i32_i24 v13, v5, s70, v13
	v_mad_i32_i24 v11, v7, s70, v11
	s_lshl_b32 s42, s2, 1
	s_mov_b32 s43, s81
	v_lshl_add_u64 v[4:5], v[12:13], 0, s[80:81]
	v_lshlrev_b32_e32 v12, 1, v8
	v_mov_b32_e32 v13, v191
	v_lshl_add_u64 v[6:7], v[10:11], 0, s[42:43]
	v_lshl_add_u64 v[6:7], v[6:7], 0, v[12:13]
	v_add_co_u32_e32 v10, vcc, s65, v6
	v_lshl_add_u64 v[4:5], v[4:5], 0, v[12:13]
	s_nop 0
	v_addc_co_u32_e32 v11, vcc, 0, v7, vcc
	v_add_co_u32_e32 v12, vcc, s79, v6
	global_load_dword v40, v[22:23], off
	global_load_ushort v1, v[6:7], off offset:2048
	global_load_dword v41, v[22:23], off offset:1024
	v_addc_co_u32_e32 v13, vcc, 0, v7, vcc
	global_load_ushort v11, v[10:11], off offset:1536
	s_nop 0
	global_load_dword v42, v[22:23], off offset:2048
	global_load_ushort v10, v[12:13], off offset:1024
	global_load_dword v43, v[22:23], off offset:3072
	v_add_co_u32_e32 v12, vcc, s82, v6
	s_mov_b32 s2, 0xd000
	s_nop 0
	v_addc_co_u32_e32 v13, vcc, 0, v7, vcc
	v_add_co_u32_e32 v16, vcc, s76, v22
	global_load_ushort v14, v[12:13], off offset:512
	s_nop 0
	v_addc_co_u32_e32 v17, vcc, 0, v23, vcc
	v_add_co_u32_e32 v20, vcc, s65, v22
	s_mov_b32 s15, 0x19000
	s_nop 0
	v_addc_co_u32_e32 v21, vcc, 0, v23, vcc
	global_load_dword v44, v[20:21], off offset:-4096
	v_add_co_u32_e32 v12, vcc, s89, v6
	v_add_u32_e32 v0, 0, v0
	s_nop 0
	v_addc_co_u32_e32 v13, vcc, 0, v7, vcc
	v_add_co_u32_e32 v18, vcc, s4, v6
	global_load_ushort v12, v[12:13], off
	s_nop 0
	global_load_dword v45, v[16:17], off offset:1024
	v_addc_co_u32_e32 v19, vcc, 0, v7, vcc
	global_load_ushort v15, v[18:19], off offset:3584
	global_load_dword v50, v[16:17], off offset:2048
	v_add_co_u32_e32 v18, vcc, s9, v6
	v_cmp_lt_i32_e64 s[46:47], 2, v9
	s_nop 0
	v_addc_co_u32_e32 v19, vcc, 0, v7, vcc
	global_load_ushort v13, v[18:19], off offset:3072
	global_load_dword v61, v[16:17], off offset:3072
	v_add_co_u32_e32 v16, vcc, s2, v6
	v_cmp_lt_i32_e64 s[48:49], 3, v9
	s_nop 0
	v_addc_co_u32_e32 v17, vcc, 0, v7, vcc
	global_load_ushort v19, v[16:17], off offset:2560
	global_load_dword v62, v[20:21], off
	v_add_co_u32_e32 v16, vcc, s5, v6
	v_cmp_lt_i32_e64 s[50:51], 4, v9
	s_nop 0
	v_addc_co_u32_e32 v17, vcc, 0, v7, vcc
	v_add_co_u32_e32 v46, vcc, s6, v6
	global_load_ushort v16, v[16:17], off offset:2048
	s_nop 0
	global_load_dword v63, v[20:21], off offset:1024
	v_addc_co_u32_e32 v47, vcc, 0, v7, vcc
	global_load_ushort v18, v[46:47], off offset:1536
	global_load_dword v64, v[20:21], off offset:2048
	v_add_co_u32_e32 v46, vcc, s7, v6
	v_cmp_lt_i32_e64 s[52:53], 5, v9
	s_nop 0
	v_addc_co_u32_e32 v47, vcc, 0, v7, vcc
	global_load_ushort v17, v[46:47], off offset:1024
	global_load_dword v65, v[20:21], off offset:3072
	v_add_co_u32_e32 v20, vcc, s86, v6
	v_cmp_lt_i32_e64 s[54:55], 7, v9
	s_nop 0
	v_addc_co_u32_e32 v21, vcc, 0, v7, vcc
	v_add_co_u32_e32 v46, vcc, s73, v22
	global_load_ushort v20, v[20:21], off offset:512
	s_nop 0
	v_addc_co_u32_e32 v47, vcc, 0, v23, vcc
	v_add_co_u32_e32 v22, vcc, s61, v6
	global_load_dword v66, v[46:47], off
	s_nop 0
	v_addc_co_u32_e32 v23, vcc, 0, v7, vcc
	global_load_ushort v21, v[22:23], off
	global_load_dword v67, v[46:47], off offset:1024
	v_add_co_u32_e32 v22, vcc, s97, v6
	v_cmp_gt_u32_e64 s[56:57], 64, v190
	s_nop 0
	v_addc_co_u32_e32 v23, vcc, 0, v7, vcc
	v_add_co_u32_e32 v48, vcc, s88, v6
	global_load_ushort v23, v[22:23], off offset:3584
	s_nop 0
	global_load_dword v68, v[46:47], off offset:2048
	v_addc_co_u32_e32 v49, vcc, 0, v7, vcc
	v_add_co_u32_e32 v6, vcc, s91, v6
	global_load_ushort v22, v[48:49], off offset:3072
	global_load_dword v69, v[46:47], off offset:3072
	v_addc_co_u32_e32 v7, vcc, 0, v7, vcc
	v_add_co_u32_e32 v46, vcc, s65, v4
	global_load_ushort v6, v[6:7], off offset:2560
	s_nop 0
	v_addc_co_u32_e32 v47, vcc, 0, v5, vcc
	global_load_ushort v7, v[46:47], off offset:1536
	global_load_ushort v57, v[4:5], off offset:2048
	v_add_co_u32_e32 v46, vcc, s79, v4
	s_nop 1
	v_addc_co_u32_e32 v47, vcc, 0, v5, vcc
	global_load_ushort v49, v[46:47], off offset:1024
	v_add_co_u32_e32 v46, vcc, s82, v4
	s_nop 1
	v_addc_co_u32_e32 v47, vcc, 0, v5, vcc
	global_load_ushort v54, v[46:47], off offset:512
	v_add_co_u32_e32 v46, vcc, s89, v4
	s_nop 1
	v_addc_co_u32_e32 v47, vcc, 0, v5, vcc
	global_load_ushort v48, v[46:47], off
	v_add_co_u32_e32 v46, vcc, s4, v4
	s_nop 1
	v_addc_co_u32_e32 v47, vcc, 0, v5, vcc
	global_load_ushort v52, v[46:47], off offset:3584
	v_add_co_u32_e32 v46, vcc, s9, v4
	s_nop 1
	v_addc_co_u32_e32 v47, vcc, 0, v5, vcc
	v_add_co_u32_e32 v58, vcc, s2, v4
	global_load_ushort v47, v[46:47], off offset:3072
	s_nop 0
	v_addc_co_u32_e32 v59, vcc, 0, v5, vcc
	global_load_ushort v51, v[58:59], off offset:2560
	v_add_co_u32_e32 v58, vcc, s5, v4
	s_nop 1
	v_addc_co_u32_e32 v59, vcc, 0, v5, vcc
	global_load_ushort v46, v[58:59], off offset:2048
	v_add_co_u32_e32 v58, vcc, s6, v4
	s_nop 1
	v_addc_co_u32_e32 v59, vcc, 0, v5, vcc
	global_load_ushort v60, v[58:59], off offset:1536
	v_add_co_u32_e32 v58, vcc, s7, v4
	s_nop 1
	v_addc_co_u32_e32 v59, vcc, 0, v5, vcc
	global_load_ushort v56, v[58:59], off offset:1024
	v_add_co_u32_e32 v58, vcc, s86, v4
	s_nop 1
	v_addc_co_u32_e32 v59, vcc, 0, v5, vcc
	v_add_co_u32_e32 v70, vcc, s61, v4
	global_load_ushort v59, v[58:59], off offset:512
	s_nop 0
	v_addc_co_u32_e32 v71, vcc, 0, v5, vcc
	global_load_ushort v55, v[70:71], off
	v_add_co_u32_e32 v70, vcc, s97, v4
	s_nop 1
	v_addc_co_u32_e32 v71, vcc, 0, v5, vcc
	global_load_ushort v58, v[70:71], off offset:3584
	v_add_co_u32_e32 v70, vcc, s88, v4
	s_nop 1
	v_addc_co_u32_e32 v71, vcc, 0, v5, vcc
	v_add_co_u32_e32 v4, vcc, s91, v4
	global_load_ushort v53, v[70:71], off offset:3072
	s_nop 0
	v_addc_co_u32_e32 v5, vcc, 0, v5, vcc
	global_load_ushort v4, v[4:5], off offset:2560
	v_mov_b32_e32 v5, v184
	s_nop 0
	v_and_b32_e32 v80, 63, v5
	v_ashrrev_i32_e32 v5, 2, v5
	v_and_b32_e32 v78, -16, v5
	v_ashrrev_i32_e32 v79, 31, v78
	v_lshl_add_u64 v[70:71], s[44:45], 0, v[78:79]
	v_mad_u64_u32 v[72:73], s[18:19], v70, s70, v[2:3]
	v_mad_i32_i24 v73, v71, s70, v73
	v_lshl_add_u64 v[70:71], v[72:73], 0, s[80:81]
	v_lshlrev_b32_e32 v72, 1, v80
	v_mov_b32_e32 v73, v191
	v_lshl_add_u64 v[70:71], v[70:71], 0, v[72:73]
	v_add_co_u32_e32 v72, vcc, s65, v70
	global_load_ushort v5, v[70:71], off offset:2560
	s_nop 0
	v_addc_co_u32_e32 v73, vcc, 0, v71, vcc
	global_load_ushort v74, v[72:73], off offset:2048
	v_add_co_u32_e32 v72, vcc, s79, v70
	v_lshlrev_b32_e32 v78, 1, v78
	s_nop 0
	v_addc_co_u32_e32 v73, vcc, 0, v71, vcc
	global_load_ushort v75, v[72:73], off offset:1536
	v_add_co_u32_e32 v72, vcc, s82, v70
	v_cmp_lt_i32_e64 s[44:45], 1, v9
	s_nop 0
	v_addc_co_u32_e32 v73, vcc, 0, v71, vcc
	global_load_ushort v76, v[72:73], off offset:1024
	v_add_co_u32_e32 v72, vcc, s89, v70
	s_nop 1
	v_addc_co_u32_e32 v73, vcc, 0, v71, vcc
	global_load_ushort v77, v[72:73], off offset:512
	v_add_co_u32_e32 v72, vcc, s67, v70
	s_nop 1
	v_addc_co_u32_e32 v73, vcc, 0, v71, vcc
	global_load_ushort v79, v[72:73], off
	v_add_co_u32_e32 v72, vcc, s9, v70
	s_nop 1
	v_addc_co_u32_e32 v73, vcc, 0, v71, vcc
	global_load_ushort v81, v[72:73], off offset:3584
	v_add_co_u32_e32 v72, vcc, s2, v70
	s_nop 1
	v_addc_co_u32_e32 v73, vcc, 0, v71, vcc
	global_load_ushort v82, v[72:73], off offset:3072
	v_add_co_u32_e32 v72, vcc, s5, v70
	s_nop 1
	v_addc_co_u32_e32 v73, vcc, 0, v71, vcc
	global_load_ushort v83, v[72:73], off offset:2560
	v_add_co_u32_e32 v72, vcc, s6, v70
	s_nop 1
	v_addc_co_u32_e32 v73, vcc, 0, v71, vcc
	global_load_ushort v84, v[72:73], off offset:2048
	v_add_co_u32_e32 v72, vcc, s7, v70
	s_nop 1
	v_addc_co_u32_e32 v73, vcc, 0, v71, vcc
	global_load_ushort v85, v[72:73], off offset:1536
	v_add_co_u32_e32 v72, vcc, s86, v70
	s_nop 1
	v_addc_co_u32_e32 v73, vcc, 0, v71, vcc
	global_load_ushort v86, v[72:73], off offset:1024
	v_add_co_u32_e32 v72, vcc, s61, v70
	s_nop 1
	v_addc_co_u32_e32 v73, vcc, 0, v71, vcc
	global_load_ushort v87, v[72:73], off offset:512
	v_add_co_u32_e32 v72, vcc, s15, v70
	s_nop 1
	v_addc_co_u32_e32 v73, vcc, 0, v71, vcc
	global_load_ushort v88, v[72:73], off
	v_add_co_u32_e32 v72, vcc, s88, v70
	s_nop 1
	v_addc_co_u32_e32 v73, vcc, 0, v71, vcc
	v_add_co_u32_e32 v70, vcc, s91, v70
	global_load_ushort v89, v[72:73], off offset:3584
	s_nop 0
	v_addc_co_u32_e32 v71, vcc, 0, v71, vcc
	global_load_ushort v90, v[70:71], off offset:3072
	s_waitcnt vmcnt(14)
	v_lshl_or_b32 v70, v74, 16, v5
	v_mul_u32_u24_e32 v5, 0x110, v80
	v_add3_u32 v5, 0, v5, v78
	s_waitcnt vmcnt(12)
	v_lshl_or_b32 v71, v76, 16, v75
	s_waitcnt vmcnt(10)
	v_lshl_or_b32 v72, v79, 16, v77
	s_waitcnt vmcnt(8)
	v_lshl_or_b32 v73, v82, 16, v81
	s_waitcnt vmcnt(6)
	v_lshl_or_b32 v74, v84, 16, v83
	s_waitcnt vmcnt(4)
	v_lshl_or_b32 v75, v86, 16, v85
	s_waitcnt vmcnt(2)
	v_lshl_or_b32 v76, v88, 16, v87
	s_waitcnt vmcnt(0)
	v_lshl_or_b32 v77, v90, 16, v89
	ds_write_b128 v5, v[70:73] offset:17408
	ds_write_b128 v5, v[74:77] offset:17424
	v_mov_b32_e32 v5, v184
	s_nop 0
	v_and_b32_e32 v80, 63, v5
	v_ashrrev_i32_e32 v5, 2, v5
	v_and_b32_e32 v78, -16, v5
	v_ashrrev_i32_e32 v79, 31, v78
	v_lshl_add_u64 v[70:71], s[40:41], 0, v[78:79]
	v_mad_u64_u32 v[2:3], s[18:19], v70, s70, v[2:3]
	v_mad_i32_i24 v3, v71, s70, v3
	v_lshl_add_u64 v[2:3], v[2:3], 0, s[42:43]
	v_lshlrev_b32_e32 v70, 1, v80
	v_mov_b32_e32 v71, v191
	v_lshl_add_u64 v[2:3], v[2:3], 0, v[70:71]
	v_add_co_u32_e32 v70, vcc, s65, v2
	global_load_ushort v5, v[2:3], off offset:2560
	s_nop 0
	v_addc_co_u32_e32 v71, vcc, 0, v3, vcc
	global_load_ushort v72, v[70:71], off offset:2048
	v_add_co_u32_e32 v70, vcc, s79, v2
	v_cmp_lt_i32_e64 s[42:43], 0, v9
	s_nop 0
	v_addc_co_u32_e32 v71, vcc, 0, v3, vcc
	global_load_ushort v73, v[70:71], off offset:1536
	v_add_co_u32_e32 v70, vcc, s82, v2
	v_cmp_lt_i32_e64 s[40:41], 6, v9
	s_nop 0
	v_addc_co_u32_e32 v71, vcc, 0, v3, vcc
	global_load_ushort v74, v[70:71], off offset:1024
	v_add_co_u32_e32 v70, vcc, s89, v2
	s_nop 1
	v_addc_co_u32_e32 v71, vcc, 0, v3, vcc
	global_load_ushort v75, v[70:71], off offset:512
	v_add_co_u32_e32 v70, vcc, s67, v2
	s_nop 1
	v_addc_co_u32_e32 v71, vcc, 0, v3, vcc
	global_load_ushort v76, v[70:71], off
	v_add_co_u32_e32 v70, vcc, s9, v2
	s_nop 1
	v_addc_co_u32_e32 v71, vcc, 0, v3, vcc
	global_load_ushort v77, v[70:71], off offset:3584
	v_add_co_u32_e32 v70, vcc, s2, v2
	s_movk_i32 s2, 0x10c
	s_nop 0
	v_addc_co_u32_e32 v71, vcc, 0, v3, vcc
	global_load_ushort v79, v[70:71], off offset:3072
	v_add_co_u32_e32 v70, vcc, s5, v2
	s_nop 1
	v_addc_co_u32_e32 v71, vcc, 0, v3, vcc
	global_load_ushort v81, v[70:71], off offset:2560
	v_add_co_u32_e32 v70, vcc, s6, v2
	s_nop 1
	v_addc_co_u32_e32 v71, vcc, 0, v3, vcc
	global_load_ushort v82, v[70:71], off offset:2048
	v_add_co_u32_e32 v70, vcc, s7, v2
	s_nop 1
	v_addc_co_u32_e32 v71, vcc, 0, v3, vcc
	global_load_ushort v83, v[70:71], off offset:1536
	v_add_co_u32_e32 v70, vcc, s86, v2
	s_nop 1
	v_addc_co_u32_e32 v71, vcc, 0, v3, vcc
	global_load_ushort v84, v[70:71], off offset:1024
	v_add_co_u32_e32 v70, vcc, s61, v2
	s_nop 1
	v_addc_co_u32_e32 v71, vcc, 0, v3, vcc
	global_load_ushort v85, v[70:71], off offset:512
	v_add_co_u32_e32 v70, vcc, s15, v2
	s_nop 1
	v_addc_co_u32_e32 v71, vcc, 0, v3, vcc
	global_load_ushort v86, v[70:71], off
	v_add_co_u32_e32 v70, vcc, s88, v2
	s_nop 1
	v_addc_co_u32_e32 v71, vcc, 0, v3, vcc
	v_add_co_u32_e32 v2, vcc, s91, v2
	global_load_ushort v87, v[70:71], off offset:3584
	s_nop 0
	v_addc_co_u32_e32 v3, vcc, 0, v3, vcc
	global_load_ushort v2, v[2:3], off offset:3072
	v_lshlrev_b32_e32 v3, 1, v78
	s_waitcnt vmcnt(14)
	v_lshl_or_b32 v70, v72, 16, v5
	v_cmp_lt_u32_e32 vcc, 63, v190
	s_waitcnt vmcnt(12)
	v_lshl_or_b32 v71, v74, 16, v73
	s_waitcnt vmcnt(10)
	v_lshl_or_b32 v72, v76, 16, v75
	s_waitcnt vmcnt(8)
	v_lshl_or_b32 v73, v79, 16, v77
	s_waitcnt vmcnt(6)
	v_lshl_or_b32 v74, v82, 16, v81
	s_waitcnt vmcnt(4)
	v_lshl_or_b32 v75, v84, 16, v83
	s_waitcnt vmcnt(2)
	v_lshl_or_b32 v76, v86, 16, v85
	s_waitcnt vmcnt(0)
	v_lshl_or_b32 v77, v2, 16, v87
	v_mul_u32_u24_e32 v2, 0x110, v80
	v_add3_u32 v2, 0, v2, v3
	ds_write_b128 v2, v[70:73] offset:54272
	ds_write_b128 v2, v[74:77] offset:54288
	v_add_f32_e32 v70, 0, v24
	v_add_f32_e32 v71, v70, v25
	v_add_f32_e32 v72, v71, v26
	v_add_f32_e32 v73, v72, v27
	v_add_f32_e32 v74, v73, v28
	v_add_f32_e32 v75, v74, v29
	v_add_f32_e32 v76, v75, v30
	v_add_f32_e32 v77, v76, v31
	v_add_f32_e32 v78, v77, v32
	v_add_f32_e32 v79, v78, v33
	v_add_f32_e32 v80, v79, v34
	v_add_f32_e32 v81, v80, v35
	v_add_f32_e32 v82, v81, v36
	v_add_f32_e32 v36, 0, v40
	v_add_f32_e32 v35, v36, v41
	v_add_f32_e32 v34, v35, v42
	v_add_f32_e32 v33, v34, v43
	v_add_f32_e32 v32, v33, v44
	v_add_f32_e32 v31, v32, v45
	v_add_f32_e32 v30, v31, v50
	v_add_f32_e32 v29, v30, v61
	v_add_f32_e32 v28, v29, v62
	v_add_f32_e32 v27, v28, v63
	v_add_f32_e32 v26, v27, v64
	v_add_f32_e32 v25, v26, v65
	v_add_f32_e32 v83, v82, v37
	v_add_f32_e32 v24, v25, v66
	v_add_f32_e32 v84, v83, v38
	v_add_f32_e32 v5, v24, v67
	v_add_f32_e32 v85, v84, v39
	v_lshl_add_u32 v37, v190, 2, 0
	v_add_f32_e32 v3, v5, v68
	ds_write_b32 v37, v85 offset:34816
	v_add_f32_e32 v2, v3, v69
	v_add_u32_e32 v37, 0x11800, v37
	ds_write_b32 v37, v2
	s_waitcnt lgkmcnt(0)
	s_barrier
	ds_read2st64_b32 v[38:39], v0 offset0:136 offset1:137
	ds_read2st64_b32 v[40:41], v0 offset0:138 offset1:139
	v_lshlrev_b32_e32 v43, 16, v54
	v_lshlrev_b32_e32 v45, 16, v51
	v_lshlrev_b32_e32 v44, 16, v47
	s_waitcnt lgkmcnt(1)
	v_add_f32_e32 v37, 0, v38
	v_cndmask_b32_e64 v38, 0, v37, s[42:43]
	v_add_f32_e32 v42, v39, v38
	v_cndmask_b32_e64 v38, v38, v42, s[44:45]
	v_add_f32_e32 v37, v37, v39
	s_waitcnt lgkmcnt(0)
	v_add_f32_e32 v39, v40, v38
	v_cndmask_b32_e64 v42, v38, v39, s[46:47]
	ds_read2st64_b32 v[38:39], v0 offset0:140 offset1:141
	v_add_f32_e32 v37, v37, v40
	v_add_f32_e32 v40, v41, v42
	v_cndmask_b32_e64 v40, v42, v40, s[48:49]
	v_add_f32_e32 v37, v37, v41
	s_waitcnt lgkmcnt(0)
	v_add_f32_e32 v41, v38, v40
	v_cndmask_b32_e64 v42, v40, v41, s[50:51]
	ds_read2st64_b32 v[40:41], v0 offset0:142 offset1:143
	v_add_f32_e32 v37, v37, v38
	v_add_f32_e32 v38, v39, v42
	v_cndmask_b32_e64 v38, v42, v38, s[52:53]
	v_add_f32_e32 v37, v37, v39
	s_waitcnt lgkmcnt(0)
	v_add_f32_e32 v39, v40, v38
	v_cndmask_b32_e64 v38, v38, v39, s[40:41]
	v_add_f32_e32 v37, v37, v40
	v_add_f32_e32 v39, v41, v38
	v_cndmask_b32_e64 v38, v38, v39, s[54:55]
	v_add_f32_e32 v37, v37, v41
	v_sub_f32_e32 v61, v37, v38
	v_sub_f32_e32 v38, v61, v70
	v_sub_f32_e32 v39, v61, v71
	v_mul_f32_e32 v38, 0x3fb8aa3b, v38
	v_mul_f32_e32 v39, 0x3fb8aa3b, v39
	v_exp_f32_e32 v38, v38
	v_exp_f32_e32 v39, v39
	v_lshlrev_b32_e32 v41, 16, v7
	v_sub_f32_e32 v7, v61, v72
	v_lshlrev_b32_e32 v40, 16, v57
	v_mul_f32_e32 v7, 0x3fb8aa3b, v7
	v_pk_mul_f32 v[38:39], v[38:39], v[40:41]
	v_exp_f32_e32 v40, v7
	v_sub_f32_e32 v7, v61, v73
	v_mul_f32_e32 v7, 0x3fb8aa3b, v7
	v_exp_f32_e32 v41, v7
	v_sub_f32_e32 v7, v61, v74
	v_lshlrev_b32_e32 v42, 16, v49
	v_mul_f32_e32 v7, 0x3fb8aa3b, v7
	v_pk_mul_f32 v[40:41], v[40:41], v[42:43]
	v_exp_f32_e32 v42, v7
	v_sub_f32_e32 v7, v61, v75
	v_mul_f32_e32 v7, 0x3fb8aa3b, v7
	v_exp_f32_e32 v43, v7
	v_sub_f32_e32 v7, v61, v76
	v_cvt_pk_bf16_f32 v38, v38, v39
	v_cvt_pk_bf16_f32 v39, v40, v41
	v_lshlrev_b32_e32 v41, 16, v52
	v_lshlrev_b32_e32 v40, 16, v48
	v_mul_f32_e32 v7, 0x3fb8aa3b, v7
	v_pk_mul_f32 v[40:41], v[42:43], v[40:41]
	v_exp_f32_e32 v42, v7
	v_sub_f32_e32 v7, v61, v77
	v_mul_f32_e32 v7, 0x3fb8aa3b, v7
	v_exp_f32_e32 v43, v7
	v_sub_f32_e32 v7, v61, v78
	v_mul_f32_e32 v7, 0x3fb8aa3b, v7
	v_cvt_pk_bf16_f32 v40, v40, v41
	v_pk_mul_f32 v[42:43], v[42:43], v[44:45]
	v_exp_f32_e32 v44, v7
	v_sub_f32_e32 v7, v61, v79
	v_mul_f32_e32 v7, 0x3fb8aa3b, v7
	v_exp_f32_e32 v45, v7
	v_sub_f32_e32 v7, v61, v80
	v_cvt_pk_bf16_f32 v41, v42, v43
	v_lshlrev_b32_e32 v43, 16, v60
	v_lshlrev_b32_e32 v42, 16, v46
	v_mul_f32_e32 v7, 0x3fb8aa3b, v7
	v_pk_mul_f32 v[42:43], v[44:45], v[42:43]
	v_exp_f32_e32 v44, v7
	v_sub_f32_e32 v7, v61, v81
	v_mul_f32_e32 v7, 0x3fb8aa3b, v7
	v_exp_f32_e32 v45, v7
	v_sub_f32_e32 v7, v61, v82
	v_lshlrev_b32_e32 v47, 16, v59
	v_lshlrev_b32_e32 v46, 16, v56
	v_mul_f32_e32 v7, 0x3fb8aa3b, v7
	v_pk_mul_f32 v[44:45], v[44:45], v[46:47]
	v_exp_f32_e32 v46, v7
	v_sub_f32_e32 v7, v61, v83
	v_mul_f32_e32 v7, 0x3fb8aa3b, v7
	v_exp_f32_e32 v47, v7
	v_sub_f32_e32 v7, v61, v84
	v_cvt_pk_bf16_f32 v42, v42, v43
	v_cvt_pk_bf16_f32 v43, v44, v45
	v_lshlrev_b32_e32 v45, 16, v58
	v_lshlrev_b32_e32 v44, 16, v55
	v_mul_f32_e32 v7, 0x3fb8aa3b, v7
	v_pk_mul_f32 v[44:45], v[46:47], v[44:45]
	v_exp_f32_e32 v46, v7
	v_sub_f32_e32 v7, v61, v85
	v_mul_f32_e32 v7, 0x3fb8aa3b, v7
	v_exp_f32_e32 v47, v7
	v_lshlrev_b32_e32 v50, 5, v9
	v_lshlrev_b32_e32 v49, 16, v4
	v_lshlrev_b32_e32 v48, 16, v53
	v_mad_u32_u24 v0, v8, s2, v0
	v_pk_mul_f32 v[46:47], v[46:47], v[48:49]
	v_add_u32_e32 v0, v0, v50
	v_cvt_pk_bf16_f32 v44, v44, v45
	v_cvt_pk_bf16_f32 v45, v46, v47
	ds_write_b128 v0, v[38:41]
	ds_write_b128 v0, v[42:45] offset:16
	s_and_saveexec_b64 s[74:75], s[56:57]
	s_cbranch_execz .LBB0_536
	v_mul_f32_e32 v4, 0x3fb8aa3b, v37
	v_exp_f32_e32 v4, v4
	v_lshl_add_u64 v[38:39], v[190:191], 2, s[34:35]
	global_store_dword v[38:39], v4, off sc1
.LBB0_536:
	s_or_b64 exec, exec, s[74:75]
	v_lshl_add_u32 v4, v8, 2, 0
	v_add_u32_e32 v4, 0x11800, v4
	ds_read2st64_b32 v[38:39], v4 offset1:1
	v_lshlrev_b32_e32 v10, 16, v10
	v_lshlrev_b32_e32 v15, 16, v15
	s_waitcnt lgkmcnt(0)
	v_add_f32_e32 v7, 0, v38
	v_cndmask_b32_e64 v37, 0, v7, s[42:43]
	v_add_f32_e32 v38, v39, v37
	v_cndmask_b32_e64 v37, v37, v38, s[44:45]
	v_add_f32_e32 v7, v7, v39
	ds_read2st64_b32 v[38:39], v4 offset0:2 offset1:3
	s_waitcnt lgkmcnt(0)
	v_add_f32_e32 v40, v38, v37
	v_cndmask_b32_e64 v37, v37, v40, s[46:47]
	v_add_f32_e32 v7, v7, v38
	v_add_f32_e32 v38, v39, v37
	v_cndmask_b32_e64 v37, v37, v38, s[48:49]
	v_add_f32_e32 v7, v7, v39
	ds_read2st64_b32 v[38:39], v4 offset0:4 offset1:5
	s_waitcnt lgkmcnt(0)
	v_add_f32_e32 v40, v38, v37
	v_cndmask_b32_e64 v37, v37, v40, s[50:51]
	v_add_f32_e32 v7, v7, v38
	v_add_f32_e32 v38, v39, v37
	v_cndmask_b32_e64 v37, v37, v38, s[52:53]
	v_add_f32_e32 v7, v7, v39
	ds_read2st64_b32 v[38:39], v4 offset0:6 offset1:7
	s_waitcnt lgkmcnt(0)
	v_add_f32_e32 v4, v38, v37
	v_cndmask_b32_e64 v4, v37, v4, s[40:41]
	v_add_f32_e32 v7, v7, v38
	v_add_f32_e32 v37, v39, v4
	v_cndmask_b32_e64 v37, v4, v37, s[54:55]
	v_add_f32_e32 v4, v7, v39
	v_sub_f32_e32 v7, v4, v37
	v_lshlrev_b32_e32 v38, 16, v1
	v_sub_f32_e32 v1, v7, v34
	v_mul_f32_e32 v1, 0x3fb8aa3b, v1
	v_sub_f32_e32 v36, v7, v36
	v_sub_f32_e32 v35, v7, v35
	v_exp_f32_e32 v34, v1
	v_sub_f32_e32 v1, v7, v33
	v_mul_f32_e32 v36, 0x3fb8aa3b, v36
	v_mul_f32_e32 v35, 0x3fb8aa3b, v35
	v_mul_f32_e32 v1, 0x3fb8aa3b, v1
	v_exp_f32_e32 v36, v36
	v_exp_f32_e32 v37, v35
	v_exp_f32_e32 v35, v1
	v_lshlrev_b32_e32 v39, 16, v11
	v_lshlrev_b32_e32 v11, 16, v14
	v_sub_f32_e32 v1, v7, v32
	v_pk_mul_f32 v[36:37], v[36:37], v[38:39]
	v_pk_mul_f32 v[10:11], v[34:35], v[10:11]
	v_mul_f32_e32 v1, 0x3fb8aa3b, v1
	v_cvt_pk_bf16_f32 v36, v36, v37
	v_cvt_pk_bf16_f32 v37, v10, v11
	v_exp_f32_e32 v10, v1
	v_sub_f32_e32 v1, v7, v31
	v_mul_f32_e32 v1, 0x3fb8aa3b, v1
	v_exp_f32_e32 v11, v1
	v_lshlrev_b32_e32 v14, 16, v12
	v_sub_f32_e32 v1, v7, v30
	v_mul_f32_e32 v1, 0x3fb8aa3b, v1
	v_pk_mul_f32 v[10:11], v[10:11], v[14:15]
	v_lshlrev_b32_e32 v15, 16, v19
	v_cvt_pk_bf16_f32 v38, v10, v11
	v_exp_f32_e32 v10, v1
	v_sub_f32_e32 v1, v7, v29
	v_mul_f32_e32 v1, 0x3fb8aa3b, v1
	v_exp_f32_e32 v11, v1
	v_lshlrev_b32_e32 v14, 16, v13
	v_sub_f32_e32 v1, v7, v28
	v_mul_f32_e32 v1, 0x3fb8aa3b, v1
	v_pk_mul_f32 v[10:11], v[10:11], v[14:15]
	v_lshlrev_b32_e32 v13, 16, v18
	v_cvt_pk_bf16_f32 v39, v10, v11
	v_exp_f32_e32 v10, v1
	v_sub_f32_e32 v1, v7, v27
	v_mul_f32_e32 v1, 0x3fb8aa3b, v1
	v_exp_f32_e32 v11, v1
	v_sub_f32_e32 v1, v7, v26
	v_lshlrev_b32_e32 v12, 16, v16
	v_mul_f32_e32 v1, 0x3fb8aa3b, v1
	v_pk_mul_f32 v[10:11], v[10:11], v[12:13]
	v_exp_f32_e32 v12, v1
	v_sub_f32_e32 v1, v7, v25
	v_mul_f32_e32 v1, 0x3fb8aa3b, v1
	v_exp_f32_e32 v13, v1
	v_lshlrev_b32_e32 v15, 16, v20
	v_lshlrev_b32_e32 v14, 16, v17
	v_sub_f32_e32 v1, v7, v24
	v_pk_mul_f32 v[12:13], v[12:13], v[14:15]
	v_mul_f32_e32 v1, 0x3fb8aa3b, v1
	v_cvt_pk_bf16_f32 v10, v10, v11
	v_cvt_pk_bf16_f32 v11, v12, v13
	v_exp_f32_e32 v12, v1
	v_sub_f32_e32 v1, v7, v5
	v_mul_f32_e32 v1, 0x3fb8aa3b, v1
	v_exp_f32_e32 v13, v1
	v_sub_f32_e32 v1, v7, v3
	v_lshlrev_b32_e32 v15, 16, v23
	v_lshlrev_b32_e32 v14, 16, v21
	v_mul_f32_e32 v1, 0x3fb8aa3b, v1
	v_pk_mul_f32 v[12:13], v[12:13], v[14:15]
	v_exp_f32_e32 v14, v1
	v_sub_f32_e32 v1, v7, v2
	v_mul_f32_e32 v1, 0x3fb8aa3b, v1
	v_exp_f32_e32 v15, v1
	v_lshlrev_b32_e32 v3, 16, v6
	v_lshlrev_b32_e32 v2, 16, v22
	v_cvt_pk_bf16_f32 v12, v12, v13
	v_pk_mul_f32 v[2:3], v[14:15], v[2:3]
	s_nop 0
	v_cvt_pk_bf16_f32 v13, v2, v3
	ds_write_b128 v0, v[36:39] offset:36864
	ds_write_b128 v0, v[10:13] offset:36880
	s_and_saveexec_b64 s[18:19], vcc
	s_xor_b64 s[40:41], exec, s[18:19]
	s_ashr_i32 s69, s68, 31
	s_or_saveexec_b64 s[40:41], s[40:41]
	v_mov_b64_e32 v[0:1], s[68:69]
	s_xor_b64 exec, exec, s[40:41]
	s_cbranch_execz .LBB0_540
	v_mul_f32_e32 v0, 0x3fb8aa3b, v4
	s_ashr_i32 s69, s68, 31
	v_exp_f32_e32 v2, v0
	s_lshl_b64 s[18:19], s[68:69], 8
	s_add_u32 s18, s10, s18
	s_addc_u32 s19, s11, s19
	v_lshl_add_u64 v[0:1], v[190:191], 2, s[18:19]
	global_store_dword v[0:1], v2, off sc1
	v_mov_b64_e32 v[0:1], s[68:69]
.LBB0_540:
	s_or_b64 exec, exec, s[40:41]
	v_lshlrev_b32_e32 v2, 1, v9
	v_and_b32_e32 v24, 2, v2
	v_ashrrev_i32_e32 v2, 3, v190
	v_and_b32_e32 v22, -16, v2
	v_bfi_b32 v4, -16, v2, v190
	v_and_b32_e32 v2, 48, v8
	v_add_u32_e32 v14, 0, v2
	s_movk_i32 s2, 0x110
	v_mad_u64_u32 v[4:5], s[18:19], v4, s2, v[14:15]
	s_waitcnt lgkmcnt(0)
	s_barrier
	ds_read_b128 v[6:9], v4
	v_and_b32_e32 v3, 15, v190
	v_or_b32_e32 v26, 1, v24
	v_lshl_or_b32 v5, v24, 4, v3
	v_lshl_or_b32 v15, v26, 4, v3
	v_mad_u32_u24 v5, v5, s2, v14
	v_mad_u32_u24 v28, v15, s2, v14
	ds_read_b128 v[10:13], v5 offset:17408
	ds_read_b128 v[14:17], v28 offset:17408
	s_waitcnt lgkmcnt(1)
	v_mfma_f32_16x16x32_bf16 v[10:13], v[6:9], v[10:13], 0
	v_ashrrev_i32_e32 v23, 31, v22
	v_lshlrev_b64 v[22:23], 2, v[22:23]
	v_lshlrev_b32_e32 v3, 8, v3
	s_waitcnt lgkmcnt(0)
	v_mfma_f32_16x16x32_bf16 v[6:9], v[6:9], v[14:17], 0
	ds_read_b128 v[14:17], v4 offset:64
	ds_read_b128 v[18:21], v5 offset:17472
	v_lshl_or_b32 v24, v24, 12, v3
	v_mov_b32_e32 v25, v191
	s_waitcnt lgkmcnt(0)
	v_mfma_f32_16x16x32_bf16 v[10:13], v[14:17], v[18:21], v[10:13]
	ds_read_b128 v[18:21], v28 offset:17472
	v_lshl_or_b32 v26, v26, 12, v3
	v_mov_b32_e32 v27, v191
	s_waitcnt lgkmcnt(0)
	v_mfma_f32_16x16x32_bf16 v[6:9], v[14:17], v[18:21], v[6:9]
	ds_read_b128 v[14:17], v4 offset:128
	ds_read_b128 v[18:21], v5 offset:17536
	v_lshlrev_b64 v[0:1], 14, v[0:1]
	v_lshl_add_u64 v[0:1], s[24:25], 0, v[0:1]
	s_waitcnt lgkmcnt(0)
	v_mfma_f32_16x16x32_bf16 v[10:13], v[14:17], v[18:21], v[10:13]
	ds_read_b128 v[18:21], v28 offset:17536
	v_lshl_add_u64 v[0:1], v[0:1], 0, v[22:23]
	v_mov_b32_e32 v3, v191
	s_waitcnt lgkmcnt(0)
	v_mfma_f32_16x16x32_bf16 v[6:9], v[14:17], v[18:21], v[6:9]
	ds_read_b128 v[14:17], v4 offset:192
	ds_read_b128 v[18:21], v5 offset:17600
	v_lshl_add_u64 v[0:1], v[0:1], 0, v[2:3]
	v_lshl_add_u64 v[2:3], v[0:1], 0, v[24:25]
	s_waitcnt lgkmcnt(0)
	v_mfma_f32_16x16x32_bf16 v[10:13], v[14:17], v[18:21], v[10:13]
	ds_read_b128 v[18:21], v28 offset:17600
	v_lshl_add_u64 v[0:1], v[0:1], 0, v[26:27]
	v_cmp_eq_u32_e32 vcc, 0, v190
	s_waitcnt lgkmcnt(0)
	v_mfma_f32_16x16x32_bf16 v[6:9], v[14:17], v[18:21], v[6:9]
	v_and_or_b32 v14, v190, 48, v22
	v_mov_b32_e32 v15, v23
	v_lshl_add_u64 v[16:17], v[14:15], 0, v[24:25]
	v_lshl_add_u64 v[16:17], s[30:31], 0, v[16:17]
	global_store_dwordx4 v[16:17], v[10:13], off sc1
	s_nop 1
	v_lshl_add_u64 v[10:11], v[14:15], 0, v[26:27]
	v_lshl_add_u64 v[10:11], s[30:31], 0, v[10:11]
	global_store_dwordx4 v[10:11], v[6:9], off sc1
	ds_read_b128 v[6:9], v4 offset:36864
	ds_read_b128 v[10:13], v5 offset:54272
	ds_read_b128 v[14:17], v28 offset:54272
	s_waitcnt lgkmcnt(1)
	v_mfma_f32_16x16x32_bf16 v[10:13], v[6:9], v[10:13], 0
	s_waitcnt lgkmcnt(0)
	v_mfma_f32_16x16x32_bf16 v[6:9], v[6:9], v[14:17], 0
	ds_read_b128 v[14:17], v4 offset:36928
	ds_read_b128 v[18:21], v5 offset:54336
	s_waitcnt lgkmcnt(0)
	v_mfma_f32_16x16x32_bf16 v[10:13], v[14:17], v[18:21], v[10:13]
	ds_read_b128 v[18:21], v28 offset:54336
	s_waitcnt lgkmcnt(0)
	v_mfma_f32_16x16x32_bf16 v[6:9], v[14:17], v[18:21], v[6:9]
	ds_read_b128 v[14:17], v4 offset:36992
	ds_read_b128 v[18:21], v5 offset:54400
	s_waitcnt lgkmcnt(0)
	v_mfma_f32_16x16x32_bf16 v[10:13], v[14:17], v[18:21], v[10:13]
	ds_read_b128 v[18:21], v28 offset:54400
	s_waitcnt lgkmcnt(0)
	v_mfma_f32_16x16x32_bf16 v[6:9], v[14:17], v[18:21], v[6:9]
	ds_read_b128 v[14:17], v4 offset:37056
	ds_read_b128 v[18:21], v5 offset:54464
	s_waitcnt lgkmcnt(0)
	v_mfma_f32_16x16x32_bf16 v[10:13], v[14:17], v[18:21], v[10:13]
	ds_read_b128 v[18:21], v28 offset:54464
	s_waitcnt lgkmcnt(0)
	v_mfma_f32_16x16x32_bf16 v[4:7], v[14:17], v[18:21], v[6:9]
	s_nop 4
	global_store_dwordx4 v[2:3], v[10:13], off sc1
	s_nop 1
	global_store_dwordx4 v[0:1], v[4:7], off sc1
	s_waitcnt vmcnt(0)
	s_barrier
	s_and_saveexec_b64 s[40:41], vcc
	s_cbranch_execz .LBB0_533
	s_mov_b64 s[42:43], exec
	v_mbcnt_lo_u32_b32 v0, s42, 0
	s_waitcnt vmcnt(0)
	s_waitcnt vmcnt(0)
	v_mbcnt_hi_u32_b32 v0, s43, v0
	v_cmp_eq_u32_e32 vcc, 0, v0
	s_and_b64 s[18:19], exec, vcc
	s_mov_b64 exec, s[18:19]
	s_cbranch_execz .LBB0_533
	s_and_b64 s[18:19], s[36:37], exec
	s_cselect_b32 s2, 2, 1
	s_bcnt1_i32_b64 s3, s[42:43]
	s_mul_i32 s2, s2, s3
	v_mov_b32_e32 v0, s2
	global_atomic_add v191, v0, s[28:29]
	v_readlane_b32 s3, v252, 3
	s_branch .LBB0_533
